# P5: workgroups 0-31 (two S5-output GEMM units) hand their last mixer-output item to workgroups 32-63
# baseline (speedup 1.0000x reference)
.LBB0_906:
	s_add_i32 s97, s97, s64
	s_sub_u32 s0, s2, 32
	s_cmp_lt_u32 s0, 32
	s_cbranch_scc0 .Lnx_1
	s_sub_u32 s1, s97, s2
	s_cmp_eq_u32 s1, 0x1200
	s_cbranch_scc0 .Lnx_1
	s_add_u32 s97, s0, 0x1100
.Lnx_1:
	s_cmp_lt_u32 s2, 32
	s_cselect_b32 s0, 0x100, 0
	s_sub_u32 s0, 0x1200, s0
	s_cmp_lt_i32 s97, s0
	s_cselect_b64 s[62:63], -1, 0
	s_and_b64 s[0:1], s[68:69], s[62:63]
	s_mov_b64 s[82:83], -1
	s_andn2_b64 vcc, exec, s[0:1]
	s_mov_b64 s[86:87], -1
	s_cbranch_vccnz .LBB0_905
	s_mul_hi_i32 s0, s97, 0x38e38e39
	s_lshr_b32 s1, s0, 31
	s_ashr_i32 s0, s0, 9
	s_add_i32 s0, s0, s1
	s_mulk_i32 s0, 0x900
	s_sub_i32 s0, s97, s0
	s_lshr_b32 s1, s0, 1
	s_bfe_i32 s0, s0, 0x100001
	s_mulk_i32 s0, 0xe39
	s_lshr_b32 s20, s0, 31
	s_lshr_b32 s0, s0, 17
	s_add_i32 s0, s0, s20
	s_mul_i32 s0, s0, 36
	s_sub_i32 s0, s1, s0
	s_sext_i32_i16 s0, s0
	s_cmp_gt_i32 s0, 3
	s_mov_b64 s[82:83], 0
	s_cselect_b64 s[86:87], -1, 0
	s_branch .LBB0_905
